# deferred w_glu/w_out_c conversion items spread over three grid barriers (4+4+6 per workgroup, waves 1..) plus two at the pass C start
# speedup vs baseline: 1.0732x; 1.0024x over previous
.LBB0_1256:
	s_waitcnt vmcnt(0)
	s_barrier
	s_cmp_eq_u32 s97, 0x100
	s_cbranch_scc0 .Lb6_skip
	v_readlane_b32 s7, v255, 2
	v_readlane_b32 s6, v255, 7
	s_nop 0
	s_lshr_b32 s7, s7, 6
	s_cmp_eq_u32 s7, 0
	s_cbranch_scc1 .Lb6_skip
	s_cmp_gt_u32 s7, 4
	s_cbranch_scc1 .Lb6_skip
	s_mov_b64 s[46:47], exec
	s_mov_b64 exec, -1
	s_add_i32 s92, s7, -1
	s_lshl_b32 s92, s92, 8
	s_add_i32 s92, s92, s6
	s_add_i32 s92, s92, 0x3800
	s_mov_b64 s[100:101], s[4:5]
	s_mov_b32 s98, 6
	s_mov_b32 s99, 0x47ff
	s_movk_i32 s48, 0x1000
	v_readlane_b32 s0, v255, 3
	v_readlane_b32 s1, v255, 4
	v_readlane_b32 s2, v255, 0
	v_readlane_b32 s3, v255, 1
	v_mov_b32_e32 v163, v0
	v_and_b32_e32 v162, 63, v0
	s_lshl_b32 s30, s7, 14
	s_nop 4
	s_branch .Ltr_f3

.Ltr_b4:
	s_cmp_eq_u32 s98, 7
	s_cbranch_scc1 .Lb7_ret
	s_cmp_eq_u32 s98, 8
	s_cbranch_scc1 .Lb8_ret
	s_branch .Lpc_back2

.LBB0_1334:
	s_cmp_eq_u32 s98, 4
	s_cbranch_scc1 .Lpc_back
	s_waitcnt vmcnt(0)
	s_barrier
	s_cmp_eq_u32 s97, 0x100
	s_cbranch_scc0 .Lb7_skip
	v_readlane_b32 s7, v255, 2
	v_readlane_b32 s6, v255, 7
	s_nop 0
	s_lshr_b32 s7, s7, 6
	s_cmp_eq_u32 s7, 0
	s_cbranch_scc1 .Lb7_skip
	s_cmp_gt_u32 s7, 4
	s_cbranch_scc1 .Lb7_skip
	s_mov_b64 s[46:47], exec
	s_mov_b64 exec, -1
	s_add_i32 s92, s7, 3
	s_lshl_b32 s92, s92, 8
	s_add_i32 s92, s92, s6
	s_add_i32 s92, s92, 0x3800
	s_mov_b64 s[100:101], s[4:5]
	s_mov_b32 s98, 7
	s_mov_b32 s99, 0x47ff
	s_movk_i32 s48, 0x1000
	v_readlane_b32 s0, v255, 3
	v_readlane_b32 s1, v255, 4
	v_readlane_b32 s2, v255, 0
	v_readlane_b32 s3, v255, 1
	v_mov_b32_e32 v163, v0
	v_and_b32_e32 v162, 63, v0
	s_lshl_b32 s30, s7, 14
	s_nop 4
	s_branch .Ltr_f4

.LBB0_1386:
	s_or_b64 exec, exec, s[0:1]
	v_readlane_b32 s2, v255, 3
	v_readlane_b32 s3, v255, 4
	s_waitcnt lgkmcnt(0)
	v_mov_b32_e32 v2, v0
	v_readlane_b32 s0, v255, 7
	s_barrier
	s_cmpk_gt_i32 s0, 0x3ff
	v_readfirstlane_b32 s6, v2
	s_cbranch_scc1 .LBB0_1414
	s_cmp_eq_u32 s97, 0x100
	s_cbranch_scc0 .Lpc_compiled
	v_readlane_b32 s6, v255, 7
	v_readlane_b32 s7, v255, 2
	s_nop 0
	s_lshr_b32 s7, s7, 6
	s_cmp_lt_u32 s7, 4
	s_cbranch_scc1 .Lpc_smp
	s_cmp_lt_u32 s7, 6
	s_cbranch_scc1 .Lpc_start
	s_add_i32 s7, s7, -6
	s_mov_b64 s[100:101], s[4:5]
	s_mov_b32 s98, 5
	s_mov_b32 s99, 0x47ff
	s_movk_i32 s48, 0x1000
	s_add_i32 s92, s7, 8
	s_lshl_b32 s92, s92, 8
	s_add_i32 s92, s92, s6
	s_add_i32 s92, s92, 0x3800
	v_readlane_b32 s0, v255, 3
	v_readlane_b32 s1, v255, 4
	v_readlane_b32 s2, v255, 0
	v_readlane_b32 s3, v255, 1
	v_and_b32_e32 v162, 63, v163
	s_lshl_b32 s30, s7, 14
	s_nop 4
	s_branch .Ltr_f4

.LBB0_1414:
	s_waitcnt vmcnt(0)
	s_barrier
	s_cmp_eq_u32 s97, 0x100
	s_cbranch_scc0 .Lb8_skip
	v_readlane_b32 s7, v255, 2
	v_readlane_b32 s6, v255, 7
	s_nop 0
	s_lshr_b32 s7, s7, 6
	s_cmp_eq_u32 s7, 0
	s_cbranch_scc1 .Lb8_skip
	s_cmp_gt_u32 s7, 6
	s_cbranch_scc1 .Lb8_skip
	s_mov_b64 s[46:47], exec
	s_mov_b64 exec, -1
	s_add_i32 s92, s7, 9
	s_lshl_b32 s92, s92, 8
	s_add_i32 s92, s92, s6
	s_add_i32 s92, s92, 0x3800
	s_mov_b64 s[100:101], s[4:5]
	s_mov_b32 s98, 8
	s_mov_b32 s99, 0x47ff
	s_movk_i32 s48, 0x1000
	v_readlane_b32 s0, v255, 3
	v_readlane_b32 s1, v255, 4
	v_readlane_b32 s2, v255, 0
	v_readlane_b32 s3, v255, 1
	v_mov_b32_e32 v163, v0
	v_and_b32_e32 v162, 63, v0
	s_lshl_b32 s30, s7, 14
	s_nop 4
	s_branch .Ltr_f4
